# out->up barrier also XCC-local; the cross-XCC WAR on the PROJ/G overlay is guarded by an asynchronous global 'proj phase done' counter
# speedup vs baseline: 1.0206x; 1.0051x over previous
.LBB0_595:
	s_waitcnt vmcnt(0)
	v_readlane_b32 s0, v255, 6
	v_readlane_b32 s1, v255, 7
	s_and_b64 vcc, exec, s[0:1]
	s_barrier
	s_cbranch_vccnz .LBB0_649
	v_mbcnt_lo_u32_b32 v0, -1, 0
	v_mbcnt_hi_u32_b32 v0, -1, v0
	s_nop 0
	v_cmp_eq_u32_e32 vcc, 0, v0
	s_and_saveexec_b64 s[4:5], vcc
	s_cbranch_execz .LBB0_648
	s_cmp_eq_u32 s33, 0x100
	s_cbranch_scc0 .Llb_skip_b3
	v_readlane_b32 s0, v253, 35
	v_readlane_b32 s1, v253, 36
	s_and_b32 s6, s2, 7
	s_lshl_b32 s6, s6, 8
	s_nop 3
	s_add_u32 s0, s0, s6
	s_addc_u32 s1, s1, 0
	s_add_u32 s0, s0, 0xf3700
	s_addc_u32 s1, s1, 0
	v_mov_b32_e32 v0, 0x2010c
	ds_read_b32 v1, v0
	v_mov_b32_e32 v2, 1
	global_atomic_add v177, v2, s[0:1]
	s_and_b32 s98, s2, 7
	s_lshl_b32 s98, s98, 8
	s_sub_u32 s98, s0, s98
	s_subb_u32 s99, s1, 0
	s_add_u32 s98, s98, 0x820
	s_addc_u32 s99, s99, 0
	global_atomic_add v177, v2, s[98:99]
	s_waitcnt lgkmcnt(0)
	v_add_u32_e32 v1, 1, v1
	ds_write_b32 v0, v1
	v_lshlrev_b32_e32 v1, 5, v1
	s_mov_b32 s12, 0

.LBB0_685:
	s_waitcnt vmcnt(0)
	v_readlane_b32 s0, v255, 6
	v_readlane_b32 s1, v255, 7
	s_and_b64 vcc, exec, s[0:1]
	s_barrier
	s_cbranch_vccnz .LBB0_739
	v_mbcnt_lo_u32_b32 v0, -1, 0
	v_mbcnt_hi_u32_b32 v0, -1, v0
	s_nop 0
	v_cmp_eq_u32_e32 vcc, 0, v0
	s_and_saveexec_b64 s[4:5], vcc
	s_cbranch_execz .LBB0_738
	s_cmp_eq_u32 s33, 0x100
	s_cbranch_scc0 .Llb_skip_b4
	v_readlane_b32 s0, v253, 35
	v_readlane_b32 s1, v253, 36
	s_and_b32 s6, s2, 7
	s_lshl_b32 s6, s6, 8
	s_nop 3
	s_add_u32 s0, s0, s6
	s_addc_u32 s1, s1, 0
	s_add_u32 s0, s0, 0xf3700
	s_addc_u32 s1, s1, 0
	v_mov_b32_e32 v0, 0x2010c
	ds_read_b32 v1, v0
	v_mov_b32_e32 v2, 1
	global_atomic_add v177, v2, s[0:1]
	s_and_b32 s98, s2, 7
	s_lshl_b32 s98, s98, 8
	s_sub_u32 s98, s0, s98
	s_subb_u32 s99, s1, 0
	s_add_u32 s98, s98, 0x820
	s_addc_u32 s99, s99, 0
	global_load_dword v3, v177, s[98:99] sc1
	s_waitcnt lgkmcnt(0)
	v_add_u32_e32 v1, 1, v1
	ds_write_b32 v0, v1
	v_lshlrev_b32_e32 v1, 5, v1
	s_mov_b32 s12, 0

.Llb_done_b4:
	v_readlane_b32 s6, v255, 5
	s_nop 3
	s_add_u32 s6, s6, 1
	s_lshl_b32 s6, s6, 8
	s_mov_b32 s12, 0
.Lp3_spin:
	v_cmp_le_u32_e32 vcc, s6, v3
	s_cbranch_vccnz .Lp3_ok
	s_sleep 1
	global_load_dword v3, v177, s[98:99] sc1
	s_waitcnt vmcnt(0)
	s_add_u32 s12, s12, 1
	s_cmp_lt_u32 s12, 0x10000
	s_cbranch_scc1 .Lp3_spin

.Llb_skip_b4:
	v_readlane_b32 s0, v254, 46
	s_waitcnt vmcnt(0) expcnt(0) lgkmcnt(0)
	s_nop 0
	v_mov_b32_e32 v0, s0
	ds_read_b32 v2, v0
	v_readlane_b32 s0, v254, 47
	s_waitcnt lgkmcnt(0)
	v_cmp_ne_u32_e32 vcc, 0, v2
	v_mov_b32_e32 v0, s0
	ds_read_b32 v0, v0
	s_cbranch_vccnz .LBB0_702
	s_mov_b32 s12, 1
	s_branch .LBB0_690
.LBB0_689:
	s_and_b64 vcc, exec, s[30:31]
	s_cbranch_vccnz .LBB0_697
